# NA: transposed V-fragment LDS reads issued ahead of the exp/cvt block in both chunk halves (second half into dedicated registers)
# speedup vs baseline: 1.0151x; 1.0151x over previous
.LBB0_1388:
	v_add3_u32 v183, v0, v152, v176
	ds_read_b64_tr_b16 v[186:187], v183 offset:2304
	ds_read_b64_tr_b16 v[184:185], v183
	ds_read_b64_tr_b16 v[190:191], v183 offset:2336
	ds_read_b64_tr_b16 v[188:189], v183 offset:32
	ds_read_b64_tr_b16 v[192:193], v183 offset:64
	ds_read_b64_tr_b16 v[196:197], v183 offset:96
	ds_read_b64_tr_b16 v[194:195], v183 offset:2368
	ds_read_b64_tr_b16 v[198:199], v183 offset:2400
	v_exp_f32_e32 v102, v102
	v_exp_f32_e32 v110, v106
	v_exp_f32_e32 v103, v103
	v_exp_f32_e32 v111, v107
	v_exp_f32_e32 v104, v104
	v_exp_f32_e32 v105, v105
	v_exp_f32_e32 v112, v108
	v_exp_f32_e32 v113, v109
	v_cvt_pk_bf16_f32 v102, v102, v103
	v_cvt_pk_bf16_f32 v103, v104, v105
	v_cvt_pk_bf16_f32 v104, v110, v111
	v_cvt_pk_bf16_f32 v105, v112, v113
	s_waitcnt lgkmcnt(6)
	v_mfma_f32_16x16x32_bf16 v[2:5], v[184:187], v[102:105], v[2:5]
	s_add_i32 s50, s50, 1
	s_addk_i32 s49, 0x2400
	s_addk_i32 s28, 0x4000
	s_waitcnt lgkmcnt(4)
	v_mfma_f32_16x16x32_bf16 v[6:9], v[188:191], v[102:105], v[6:9]
	s_cmp_lg_u32 s28, 0x20000
	s_waitcnt lgkmcnt(1)
	v_mfma_f32_16x16x32_bf16 v[10:13], v[192:195], v[102:105], v[10:13]
	s_waitcnt lgkmcnt(0)
	v_mfma_f32_16x16x32_bf16 v[14:17], v[196:199], v[102:105], v[14:17]
	v_mfma_f32_16x16x32_bf16 v[98:101], v[18:21], v[102:105], v[98:101]
	s_cbranch_scc0 .LBB0_1384

.LBB0_1408:
	v_add3_u32 v182, v19, v152, v176
	ds_read_b64_tr_b16 v[124:125], v182 offset:2304
	ds_read_b64_tr_b16 v[122:123], v182
	ds_read_b64_tr_b16 v[128:129], v182 offset:2336
	ds_read_b64_tr_b16 v[126:127], v182 offset:32
	ds_read_b64_tr_b16 v[130:131], v182 offset:64
	ds_read_b64_tr_b16 v[178:179], v182 offset:96
	ds_read_b64_tr_b16 v[132:133], v182 offset:2368
	ds_read_b64_tr_b16 v[180:181], v182 offset:2400
	v_exp_f32_e32 v0, v0
	v_exp_f32_e32 v21, v111
	v_exp_f32_e32 v20, v114
	v_exp_f32_e32 v111, v115
	v_exp_f32_e32 v114, v112
	v_exp_f32_e32 v113, v113
	v_cvt_pk_bf16_f32 v112, v0, v21
	v_exp_f32_e32 v115, v116
	v_exp_f32_e32 v116, v117
	v_cvt_pk_bf16_f32 v113, v114, v113
	v_cvt_pk_bf16_f32 v114, v20, v111
	v_mov_b32_e32 v19, v18
	v_mov_b32_e32 v20, v18
	v_mov_b32_e32 v21, v18
	v_cvt_pk_bf16_f32 v115, v115, v116
	s_andn2_b64 vcc, exec, s[36:37]
	v_mov_b32_e32 v0, s49
	s_waitcnt lgkmcnt(6)
	v_mfma_f32_16x16x32_bf16 v[2:5], v[122:125], v[112:115], v[2:5]
	s_waitcnt lgkmcnt(4)
	v_mfma_f32_16x16x32_bf16 v[6:9], v[126:129], v[112:115], v[6:9]
	s_waitcnt lgkmcnt(1)
	v_mfma_f32_16x16x32_bf16 v[10:13], v[130:133], v[112:115], v[10:13]
	s_waitcnt lgkmcnt(0)
	v_mfma_f32_16x16x32_bf16 v[14:17], v[178:181], v[112:115], v[14:17]
	v_mfma_f32_16x16x32_bf16 v[98:101], v[18:21], v[112:115], v[98:101]
	s_cbranch_vccnz .LBB0_1388
	v_lshl_add_u32 v0, v110, 6, v172
	v_mul_i32_i24_e32 v0, 0x90, v0
	s_branch .LBB0_1388
